# hand-written grid barrier: per-XCD election kept, every workgroup waits on the top arrival counter directly
# baseline (speedup 1.0000x reference)
.LBB0_24:
	v_writelane_b32 v255, s0, 24
	s_cmp_le_i32 s0, s66
	s_cbranch_scc1 .LBB0_78
	s_waitcnt vmcnt(0)
	s_barrier
	s_mov_b64 s[0:1], exec
	v_readlane_b32 s2, v252, 8
	v_readlane_b32 s3, v252, 9
	s_and_b64 s[2:3], s[0:1], s[2:3]
	s_mov_b64 exec, s[2:3]
	s_cbranch_execz .LBB0_77
	v_mov_b32_e32 v0, 0x22000
	s_waitcnt lgkmcnt(0)
	ds_read2_b32 v[2:3], v0 offset1:1
	s_getreg_b32 s2, hwreg(HW_REG_XCC_ID, 0, 4)
	s_lshl_b32 s2, s2, 8
	s_add_u32 s20, s64, 0x1f600400
	s_addc_u32 s21, s65, 0
	s_add_u32 s40, s20, s2
	s_addc_u32 s41, s21, 0
	s_add_u32 s40, s40, 0x1000
	s_addc_u32 s41, s41, 0
	s_add_u32 s42, s20, 0x3000
	s_addc_u32 s43, s21, 0
	v_readlane_b32 s44, v255, 24
	s_sub_i32 s44, s44, s66
	s_waitcnt lgkmcnt(0)
	v_readfirstlane_b32 s28, v2
	v_readfirstlane_b32 s29, v3
	s_cmp_lg_u32 s28, 0
	s_cbranch_scc1 .Lgb_have
	s_load_dword s45, s[74:75], 0x0
	s_mov_b32 s46, 0
.Lgb_disc:
	global_load_dword v4, v177, s[20:21] offset:0 sc1
	global_load_dword v5, v177, s[20:21] offset:256 sc1
	global_load_dword v6, v177, s[20:21] offset:512 sc1
	global_load_dword v7, v177, s[20:21] offset:768 sc1
	global_load_dword v8, v177, s[20:21] offset:1024 sc1
	global_load_dword v9, v177, s[20:21] offset:1280 sc1
	global_load_dword v10, v177, s[20:21] offset:1536 sc1
	global_load_dword v11, v177, s[20:21] offset:1792 sc1
	global_load_dword v12, v177, s[20:21] offset:2048 sc1
	global_load_dword v13, v177, s[20:21] offset:2304 sc1
	global_load_dword v14, v177, s[20:21] offset:2560 sc1
	global_load_dword v15, v177, s[20:21] offset:2816 sc1
	global_load_dword v16, v177, s[20:21] offset:3072 sc1
	global_load_dword v17, v177, s[20:21] offset:3328 sc1
	global_load_dword v18, v177, s[20:21] offset:3584 sc1
	global_load_dword v19, v177, s[20:21] offset:3840 sc1
	s_waitcnt vmcnt(0) lgkmcnt(0)
	s_mov_b32 s6, 0
	s_mov_b32 s7, 0
	v_readfirstlane_b32 s3, v4
	s_add_i32 s6, s6, s3
	s_cmp_lg_u32 s3, 0
	s_addc_u32 s7, s7, 0
	v_readfirstlane_b32 s3, v5
	s_add_i32 s6, s6, s3
	s_cmp_lg_u32 s3, 0
	s_addc_u32 s7, s7, 0
	v_readfirstlane_b32 s3, v6
	s_add_i32 s6, s6, s3
	s_cmp_lg_u32 s3, 0
	s_addc_u32 s7, s7, 0
	v_readfirstlane_b32 s3, v7
	s_add_i32 s6, s6, s3
	s_cmp_lg_u32 s3, 0
	s_addc_u32 s7, s7, 0
	v_readfirstlane_b32 s3, v8
	s_add_i32 s6, s6, s3
	s_cmp_lg_u32 s3, 0
	s_addc_u32 s7, s7, 0
	v_readfirstlane_b32 s3, v9
	s_add_i32 s6, s6, s3
	s_cmp_lg_u32 s3, 0
	s_addc_u32 s7, s7, 0
	v_readfirstlane_b32 s3, v10
	s_add_i32 s6, s6, s3
	s_cmp_lg_u32 s3, 0
	s_addc_u32 s7, s7, 0
	v_readfirstlane_b32 s3, v11
	s_add_i32 s6, s6, s3
	s_cmp_lg_u32 s3, 0
	s_addc_u32 s7, s7, 0
	v_readfirstlane_b32 s3, v12
	s_add_i32 s6, s6, s3
	s_cmp_lg_u32 s3, 0
	s_addc_u32 s7, s7, 0
	v_readfirstlane_b32 s3, v13
	s_add_i32 s6, s6, s3
	s_cmp_lg_u32 s3, 0
	s_addc_u32 s7, s7, 0
	v_readfirstlane_b32 s3, v14
	s_add_i32 s6, s6, s3
	s_cmp_lg_u32 s3, 0
	s_addc_u32 s7, s7, 0
	v_readfirstlane_b32 s3, v15
	s_add_i32 s6, s6, s3
	s_cmp_lg_u32 s3, 0
	s_addc_u32 s7, s7, 0
	v_readfirstlane_b32 s3, v16
	s_add_i32 s6, s6, s3
	s_cmp_lg_u32 s3, 0
	s_addc_u32 s7, s7, 0
	v_readfirstlane_b32 s3, v17
	s_add_i32 s6, s6, s3
	s_cmp_lg_u32 s3, 0
	s_addc_u32 s7, s7, 0
	v_readfirstlane_b32 s3, v18
	s_add_i32 s6, s6, s3
	s_cmp_lg_u32 s3, 0
	s_addc_u32 s7, s7, 0
	v_readfirstlane_b32 s3, v19
	s_add_i32 s6, s6, s3
	s_cmp_lg_u32 s3, 0
	s_addc_u32 s7, s7, 0
	s_cmp_eq_u32 s6, s45
	s_cbranch_scc1 .Lgb_disc_done
	s_sleep 1
	s_add_i32 s46, s46, 1
	s_cmp_lt_u32 s46, 0x40000
	s_cbranch_scc1 .Lgb_disc
.Lgb_disc_done:
	s_lshr_b32 s3, s2, 6
	v_mov_b32_e32 v1, s3
	s_mov_b32 s29, s7
	s_max_u32 s29, s29, 1
	v_mov_b32_e32 v3, s29
	global_load_dword v2, v177, s[40:41] offset:-4096 sc1
	s_waitcnt vmcnt(0)
	v_readfirstlane_b32 s28, v2
	s_max_u32 s28, s28, 1
	v_mov_b32_e32 v2, s28
	ds_write2_b32 v0, v2, v3 offset1:1
.Lgb_have:
	global_atomic_add v0, v177, v181, s[40:41] sc0
	s_mul_i32 s38, s44, s28
	s_mul_i32 s39, s44, s29
	s_waitcnt vmcnt(0)
	v_readfirstlane_b32 s3, v0
	s_add_i32 s3, s3, 1
	s_cmp_eq_u32 s3, s38
	s_cbranch_scc0 .Lgb_wait
	buffer_wbl2 sc1
	s_waitcnt vmcnt(0)
	global_atomic_add v177, v181, s[42:43]
.Lgb_wait:
	s_mov_b32 s46, 0
.Lgb_spin:
	global_load_dword v0, v177, s[42:43] sc1
	s_waitcnt vmcnt(0)
	v_readfirstlane_b32 s3, v0
	s_cmp_ge_u32 s3, s39
	s_cbranch_scc1 .Lgb_done
	s_sleep 1
	s_add_i32 s46, s46, 1
	s_cmp_lt_u32 s46, 0x40000
	s_cbranch_scc1 .Lgb_spin
.Lgb_done:
	buffer_inv sc1
	s_waitcnt lgkmcnt(0)
